# SLC and FoX fast paths: packed P fragments kept in dedicated registers instead of reusing score registers
# speedup vs baseline: 1.0017x; 1.0017x over previous
; #define LAS __attribute__((address_space(3)))
; __device__ __forceinline__ unsigned pack2(float lo, float hi) { unsigned r; asm volatile("v_cvt_pk_bf16_f32 %0, %1, %2" : "=v"(r) : "v"(lo), "v"(hi)); return r; }
; __device__ __forceinline__ float fexp2(float x) { return __builtin_amdgcn_exp2f(x); }
; __device__ __forceinline__ f32x16 mfma32(bf16x8 a, bf16x8 b, f32x16 c) { return __builtin_amdgcn_mfma_f32_32x32x16_bf16(a, b, c, 0, 0, 0); }
; template <int MODE, int DK, bool PASS2> ...
;     ...
;                     float ps0 = 0.f, ps1 = 0.f;
; #pragma unroll
;                     for (int r = 0; r < 16; ++r) {
;                         s0[r] = fexp2(__builtin_fmaf(s0[r], sl2, nm)); s1[r] = fexp2(__builtin_fmaf(s1[r], sl2, nm));
;                         ps0 += s0[r]; ps1 += s1[r];
;                     }
;                     l_run = l_run * alpha + (ps0 + ps1);
;     ...
;                 if (!PASS2) {
;                     bf16x8 pf[4];
; #pragma unroll
;                     for (int k2 = 0; k2 < 4; ++k2) {
;                         u32x4 pk;
; #pragma unroll
;                         for (int e = 0; e < 4; ++e) pk[e] = (k2 < 2) ? pack2(s0[(k2 & 1) * 8 + 2 * e], s0[(k2 & 1) * 8 + 2 * e + 1]) : pack2(s1[(k2 & 1) * 8 + 2 * e], s1[(k2 & 1) * 8 + 2 * e + 1]);
;                         pf[k2] = __builtin_bit_cast(bf16x8, pk);
;                     }
;                     const LAS unsigned char* vb = lds + F_VB0 + buf * F_VBS + ql * 144 + g * 16;
;                     __builtin_amdgcn_s_setprio(1);
; #pragma unroll
;                     for (int db = 0; db < 4; ++db)
; #pragma unroll
;                         for (int k2 = 0; k2 < 4; ++k2) {
;                             const bf16x8 vf = *(const LAS bf16x8*)(vb + db * 32 * 144 + k2 * 32);
;                             O[db] = mfma32(vf, pf[k2], O[db]);
;                             if (k2 == 3 && (db & 1)) __builtin_amdgcn_sched_barrier(0);
;                         }
;                     __builtin_amdgcn_s_setprio(0);
;                     if (MODE == M_FOX) {
;                         if (has) { const float cn = cg2[jn * 64 + 63]; dead = __builtin_amdgcn_ballot_w64(!((qnb - cn) - m_run < -160.0f)) == 0ull; }
;                     }
.Lfast_fox_norescale:
	v_fma_f32 v118, v98, s83, -v4
	v_fma_f32 v119, v99, s83, -v4
	v_exp_f32_e32 v6, v118
	v_exp_f32_e32 v7, v119
	v_fma_f32 v120, v100, s83, -v4
	v_fma_f32 v121, v101, s83, -v4
	v_exp_f32_e32 v8, v120
	v_exp_f32_e32 v9, v121
	v_add_f32_e32 v122, v6, v7
	v_fma_f32 v118, v102, s83, -v4
	v_fma_f32 v119, v103, s83, -v4
	v_exp_f32_e32 v114, v118
	v_exp_f32_e32 v115, v119
	v_cvt_pk_bf16_f32 v128, v6, v7
	v_add_f32_e32 v122, v122, v8
	v_fma_f32 v120, v104, s83, -v4
	v_add_f32_e32 v122, v122, v9
	v_fma_f32 v121, v105, s83, -v4
	v_exp_f32_e32 v116, v120
	v_exp_f32_e32 v117, v121
	v_cvt_pk_bf16_f32 v129, v8, v9
	v_add_f32_e32 v122, v122, v114
	v_add_f32_e32 v122, v122, v115
	v_cvt_pk_bf16_f32 v130, v114, v115
	v_add_f32_e32 v122, v122, v116
	v_add_f32_e32 v122, v122, v117
	v_cvt_pk_bf16_f32 v131, v116, v117
	s_setprio 1
	v_fma_f32 v118, v106, s83, -v4
	v_fma_f32 v119, v107, s83, -v4
	s_waitcnt lgkmcnt(2)
	v_mfma_f32_32x32x16_bf16 v[66:81], v[240:243], v[128:131], v[66:81]
	v_exp_f32_e32 v6, v118
	v_exp_f32_e32 v7, v119
	v_fma_f32 v120, v108, s83, -v4
	v_fma_f32 v121, v109, s83, -v4
	v_exp_f32_e32 v8, v120
	v_exp_f32_e32 v9, v121
	s_waitcnt lgkmcnt(1)
	v_mfma_f32_32x32x16_bf16 v[50:65], v[244:247], v[128:131], v[50:65]
	ds_read_b128 v[240:243], v252 offset:48640
	v_add_f32_e32 v122, v122, v6
	v_fma_f32 v118, v110, s83, -v4
	v_add_f32_e32 v122, v122, v7
	v_fma_f32 v119, v111, s83, -v4
	v_exp_f32_e32 v114, v118
	v_exp_f32_e32 v115, v119
	s_waitcnt lgkmcnt(1)
	v_mfma_f32_32x32x16_bf16 v[34:49], v[248:251], v[128:131], v[34:49]
	ds_read_b128 v[244:247], v252 offset:34848
	v_cvt_pk_bf16_f32 v132, v6, v7
	v_add_f32_e32 v122, v122, v8
	v_fma_f32 v120, v112, s83, -v4
	v_add_f32_e32 v122, v122, v9
	v_fma_f32 v121, v113, s83, -v4
	v_exp_f32_e32 v116, v120
	s_waitcnt lgkmcnt(1)
	v_mfma_f32_32x32x16_bf16 v[18:33], v[240:243], v[128:131], v[18:33]
	ds_read_b128 v[248:251], v252 offset:39456
	v_exp_f32_e32 v117, v121
	v_cvt_pk_bf16_f32 v133, v8, v9
	v_add_f32_e32 v122, v122, v114
	v_add_f32_e32 v122, v122, v115
	v_cvt_pk_bf16_f32 v134, v114, v115
	v_add_f32_e32 v122, v122, v116
	v_add_f32_e32 v122, v122, v117
	v_cvt_pk_bf16_f32 v135, v116, v117
	v_fma_f32 v118, v82, s83, -v4
	v_fma_f32 v119, v83, s83, -v4
	s_waitcnt lgkmcnt(1)
	v_mfma_f32_32x32x16_bf16 v[66:81], v[244:247], v[132:135], v[66:81]
	ds_read_b128 v[240:243], v252 offset:44064
	v_exp_f32_e32 v6, v118
	v_exp_f32_e32 v7, v119
	v_fma_f32 v120, v84, s83, -v4
	v_fma_f32 v121, v85, s83, -v4
	v_exp_f32_e32 v8, v120
	v_exp_f32_e32 v9, v121
	s_waitcnt lgkmcnt(1)
	v_mfma_f32_32x32x16_bf16 v[50:65], v[248:251], v[132:135], v[50:65]
	ds_read_b128 v[244:247], v252 offset:48672
	v_add_f32_e32 v123, v6, v7
	v_fma_f32 v118, v86, s83, -v4
	v_fma_f32 v119, v87, s83, -v4
	v_exp_f32_e32 v114, v118
	v_exp_f32_e32 v115, v119
	v_cvt_pk_bf16_f32 v136, v6, v7
	s_waitcnt lgkmcnt(1)
	v_mfma_f32_32x32x16_bf16 v[34:49], v[240:243], v[132:135], v[34:49]
	ds_read_b128 v[248:251], v252 offset:34880
	v_add_f32_e32 v123, v123, v8
	v_fma_f32 v120, v88, s83, -v4
	v_add_f32_e32 v123, v123, v9
	v_fma_f32 v121, v89, s83, -v4
	v_exp_f32_e32 v116, v120
	v_exp_f32_e32 v117, v121
	s_waitcnt lgkmcnt(1)
	v_mfma_f32_32x32x16_bf16 v[18:33], v[244:247], v[132:135], v[18:33]
	ds_read_b128 v[240:243], v252 offset:39488
	v_cvt_pk_bf16_f32 v137, v8, v9
	v_add_f32_e32 v123, v123, v114
	v_add_f32_e32 v123, v123, v115
	v_cvt_pk_bf16_f32 v138, v114, v115
	v_add_f32_e32 v123, v123, v116
	v_add_f32_e32 v123, v123, v117
	v_cvt_pk_bf16_f32 v139, v116, v117
	v_fma_f32 v118, v90, s83, -v4
	v_fma_f32 v119, v91, s83, -v4
	s_waitcnt lgkmcnt(1)
	v_mfma_f32_32x32x16_bf16 v[66:81], v[248:251], v[136:139], v[66:81]
	ds_read_b128 v[244:247], v252 offset:44096
	v_exp_f32_e32 v6, v118
	v_exp_f32_e32 v7, v119
	v_fma_f32 v120, v92, s83, -v4
	v_fma_f32 v121, v93, s83, -v4
	v_exp_f32_e32 v8, v120
	v_exp_f32_e32 v9, v121
	s_waitcnt lgkmcnt(1)
	v_mfma_f32_32x32x16_bf16 v[50:65], v[240:243], v[136:139], v[50:65]
	ds_read_b128 v[248:251], v252 offset:48704
	v_add_f32_e32 v123, v123, v6
	v_fma_f32 v118, v94, s83, -v4
	v_add_f32_e32 v123, v123, v7
	v_fma_f32 v119, v95, s83, -v4
	v_exp_f32_e32 v114, v118
	v_exp_f32_e32 v115, v119
	s_waitcnt lgkmcnt(1)
	v_mfma_f32_32x32x16_bf16 v[34:49], v[244:247], v[136:139], v[34:49]
	ds_read_b128 v[240:243], v252 offset:34912
	v_cvt_pk_bf16_f32 v140, v6, v7
	v_add_f32_e32 v123, v123, v8
	v_fma_f32 v120, v96, s83, -v4
	v_add_f32_e32 v123, v123, v9
	v_fma_f32 v121, v97, s83, -v4
	v_exp_f32_e32 v116, v120
	s_waitcnt lgkmcnt(1)
	v_mfma_f32_32x32x16_bf16 v[18:33], v[248:251], v[136:139], v[18:33]
	ds_read_b128 v[244:247], v252 offset:39520
	v_exp_f32_e32 v117, v121
	v_cvt_pk_bf16_f32 v141, v8, v9
	v_add_f32_e32 v123, v123, v114
	v_add_f32_e32 v123, v123, v115
	v_cvt_pk_bf16_f32 v142, v114, v115
	v_add_f32_e32 v123, v123, v116
	v_add_f32_e32 v123, v123, v117
	v_cvt_pk_bf16_f32 v143, v116, v117
	v_add_f32_e32 v5, v122, v123
	s_waitcnt lgkmcnt(1)
	v_mfma_f32_32x32x16_bf16 v[66:81], v[240:243], v[140:143], v[66:81]
	ds_read_b128 v[248:251], v252 offset:44128
	v_fmac_f32_e32 v5, v238, v2
	s_waitcnt lgkmcnt(1)
	v_mfma_f32_32x32x16_bf16 v[50:65], v[244:247], v[140:143], v[50:65]
	ds_read_b128 v[240:243], v252 offset:48736
	s_waitcnt lgkmcnt(1)
	v_mfma_f32_32x32x16_bf16 v[34:49], v[248:251], v[140:143], v[34:49]
	s_waitcnt lgkmcnt(0)
	v_mfma_f32_32x32x16_bf16 v[18:33], v[240:243], v[140:143], v[18:33]
	s_setprio 0
	s_and_b64 vcc, exec, s[10:11]
	s_cbranch_vccnz .Lpostpv_fox
	s_waitcnt vmcnt(0)
	v_mov_b32_e32 v2, v145
	s_branch .Lfox_cn_ready
	s_branch .Lpostpv_fox

; template <int MODE, int DK, bool PASS2> ...
;     ...
;             if (MODE == M_SLC) {
;                 selbit = ((((const LAS unsigned*)impw)[j >> 5] >> (j & 31)) & 1u) != 0u;
;                 active = active && (__builtin_amdgcn_ballot_w64(selbit) != 0ull);
;             }
;             if (active) {
;                 f32x16 s0, s1;
;                 if (MODE == M_FOX) {
;                     const LAS float* ct = (const LAS float*)(lds + F_CT + buf * 256) + 8 * g;
; #pragma unroll
;                     for (int q4 = 0; q4 < 4; ++q4) {
;                         const f32x4 a = *(const LAS f32x4*)(ct + (q4 >> 1) * 16 + (q4 & 1) * 4), b = *(const LAS f32x4*)(ct + 32 + (q4 >> 1) * 16 + (q4 & 1) * 4);
; #pragma unroll
;                         for (int e = 0; e < 4; ++e) { s0[q4 * 4 + e] = a[e]; s1[q4 * 4 + e] = b[e]; }
;                     }
;                 } else { s0 = (f32x16)(0.f); s1 = (f32x16)(0.f); }
;                 const LAS unsigned char* kb = lds + F_KB0 + buf * F_KBS + g * 16 + prow * KSTR;
;                 __builtin_amdgcn_s_setprio(1);
; #pragma unroll
;                 for (int kk = 0; kk < DK / 16; ++kk) {
;                     const bf16x8 a0 = *(const LAS bf16x8*)(kb + kk * 32);
;                     const bf16x8 a1 = *(const LAS bf16x8*)(kb + 32 * KSTR + kk * 32);
;                     s0 = mfma32(a0, qf[kk], s0); s1 = mfma32(a1, qf[kk], s1);
;                 }
;                 __builtin_amdgcn_s_setprio(0);
;                 const bool need_causal = pos_max > t_wmin;
;                 const bool need_bias = (MODE != M_FOX) && ((t_wmin - pos_max) < 128);
;                 const bool need_win = (MODE == M_WIN) && (t_wmax - pos_min >= 512);
;                 if (!PASS2 && !(need_causal || need_bias || need_win)) {
;                     float mx = fmaxf(s0[0], s1[0]);
; #pragma unroll
;                     for (int r = 1; r < 16; ++r) mx = fmax3(mx, s0[r], s1[r]);
;                     if (MODE == M_SLC) mx = selbit ? mx : NEG;
;                     mx = xhalf_max(mx);
;                     const float mxs = mx * sl2;
;                     const float mn = (mxs > m_run + 8.0f) ? mxs : m_run;
;                     const float alpha = fexp2(m_run - mn);
;                     m_run = mn;
;                     float nm = -mn;
;                     if (MODE == M_SLC) nm = selbit ? nm : -__builtin_inff();
.LBB0_2597:
	s_lshl_b32 s78, s48, 6
	v_cmp_le_i32_e32 vcc, s78, v206
	s_and_saveexec_b64 s[38:39], vcc
	s_cbranch_execz .LBB0_2610
	s_ashr_i32 s4, s48, 5
	s_cmp_eq_u32 s4, s101
	s_cbranch_scc1 .Lslc_selhit
	v_lshl_add_u32 v252, s4, 2, v164
	s_mov_b32 s101, s4
	ds_read_b32 v252, v252
	s_waitcnt lgkmcnt(0)
.Lslc_selhit:
	s_and_b32 s4, s48, 31
	v_lshrrev_b32_e32 v4, s48, v252
	v_bfe_u32 v2, v252, s4, 1
	v_and_b32_e32 v4, 1, v4
	v_cmp_ne_u32_e32 vcc, 0, v2
	v_cmp_eq_u32_e64 s[4:5], 1, v4
	s_cbranch_vccz .LBB0_2610
	s_mul_i32 s6, s74, 0x4400
	s_or_b32 s48, s78, 63
	v_add_u32_e32 v2, s6, v215
	s_setprio 1
	ds_read_b128 v[4:7], v2
	ds_read_b128 v[8:11], v2 offset:32
	s_waitcnt lgkmcnt(1)
	v_mfma_f32_32x32x16_bf16 v[98:113], v[4:7], v[114:117], 0
	ds_read_b128 v[4:7], v2 offset:8704
	ds_read_b128 v[12:15], v2 offset:8736
	s_waitcnt lgkmcnt(1)
	v_mfma_f32_32x32x16_bf16 v[82:97], v[4:7], v[114:117], 0
	v_mfma_f32_32x32x16_bf16 v[98:113], v[8:11], v[118:121], v[98:113]
	ds_read_b128 v[4:7], v2 offset:64
	ds_read_b128 v[8:11], v2 offset:96
	s_waitcnt lgkmcnt(2)
	v_mfma_f32_32x32x16_bf16 v[82:97], v[12:15], v[118:121], v[82:97]
	s_waitcnt lgkmcnt(1)
	v_mfma_f32_32x32x16_bf16 v[98:113], v[4:7], v[122:125], v[98:113]
	ds_read_b128 v[4:7], v2 offset:8768
	ds_read_b128 v[12:15], v2 offset:8800
	s_waitcnt lgkmcnt(1)
	v_mfma_f32_32x32x16_bf16 v[82:97], v[4:7], v[122:125], v[82:97]
	v_mfma_f32_32x32x16_bf16 v[98:113], v[8:11], v[126:129], v[98:113]
	ds_read_b128 v[4:7], v2 offset:128
	ds_read_b128 v[8:11], v2 offset:160
	s_waitcnt lgkmcnt(2)
	v_mfma_f32_32x32x16_bf16 v[82:97], v[12:15], v[126:129], v[82:97]
	s_waitcnt lgkmcnt(1)
	v_mfma_f32_32x32x16_bf16 v[98:113], v[4:7], v[130:133], v[98:113]
	ds_read_b128 v[4:7], v2 offset:8832
	ds_read_b128 v[12:15], v2 offset:8864
	s_waitcnt lgkmcnt(1)
	v_mfma_f32_32x32x16_bf16 v[82:97], v[4:7], v[130:133], v[82:97]
	v_mfma_f32_32x32x16_bf16 v[98:113], v[8:11], v[134:137], v[98:113]
	ds_read_b128 v[4:7], v2 offset:192
	ds_read_b128 v[8:11], v2 offset:224
	s_waitcnt lgkmcnt(2)
	v_mfma_f32_32x32x16_bf16 v[82:97], v[12:15], v[134:137], v[82:97]
	s_waitcnt lgkmcnt(1)
	v_mfma_f32_32x32x16_bf16 v[98:113], v[4:7], v[138:141], v[98:113]
	ds_read_b128 v[4:7], v2 offset:8896
	ds_read_b128 v[12:15], v2 offset:8928
	s_waitcnt lgkmcnt(1)
	v_mfma_f32_32x32x16_bf16 v[82:97], v[4:7], v[138:141], v[82:97]
	v_mfma_f32_32x32x16_bf16 v[98:113], v[8:11], v[142:145], v[98:113]
	s_waitcnt lgkmcnt(0)
	v_mfma_f32_32x32x16_bf16 v[82:97], v[12:15], v[142:145], v[82:97]
	s_setprio 0
	v_min_i32_e32 v2, v199, v207
	v_cmp_gt_i32_e64 s[6:7], s48, v207
	v_cmp_le_i32_e32 vcc, s48, v2
	v_add_f32_e32 v2, 0x41000000, v217
	s_and_saveexec_b64 s[48:49], vcc
	s_xor_b64 s[48:49], exec, s[48:49]
	s_cbranch_execz .LBB0_2603
	s_cmp_eq_u64 s[48:49], 0
	s_cbranch_scc1 .Lfast_slc
	s_nop 3
	v_max_f32_e32 v4, v82, v82
	v_max_f32_e32 v5, v98, v98
	v_max_f32_e32 v4, v5, v4
	v_max3_f32 v4, v4, v99, v83
	s_nop 0
	v_max3_f32 v4, v4, v100, v84
	s_nop 0
	v_max3_f32 v4, v4, v101, v85
	s_nop 0
	v_max3_f32 v4, v4, v102, v86
	s_nop 0
	v_max3_f32 v4, v4, v103, v87
	s_nop 0
	v_max3_f32 v4, v4, v104, v88
	s_nop 0
	v_max3_f32 v4, v4, v105, v89
	s_nop 0
	v_max3_f32 v4, v4, v106, v90
	s_nop 0
	v_max3_f32 v4, v4, v107, v91
	s_nop 0
	v_max3_f32 v4, v4, v108, v92
	s_nop 0
	v_max3_f32 v4, v4, v109, v93
	s_nop 0
	v_max3_f32 v4, v4, v110, v94
	s_nop 0
	v_max3_f32 v4, v4, v111, v95
	s_nop 0
	v_max3_f32 v4, v4, v112, v96
	s_nop 0
	v_max3_f32 v4, v4, v113, v97
	s_nop 0
	v_cndmask_b32_e64 v4, v194, v4, s[4:5]
	v_mov_b32_e32 v5, v4
	s_nop 1
	v_permlane32_swap_b32_e32 v4, v5
	v_max_f32_e32 v5, v5, v5
	v_max_f32_e32 v4, v4, v4
	v_max_f32_e32 v4, v4, v5
	v_mul_f32_e32 v4, 0x3e0293ee, v4
	v_cmp_gt_f32_e32 vcc, v4, v2
	s_nop 1
	v_cndmask_b32_e32 v218, v217, v4, vcc
	v_sub_f32_e32 v2, v217, v218
	v_exp_f32_e32 v2, v2
	s_nop 0
	v_cmp_neq_f32_e32 vcc, 1.0, v2
	s_cbranch_vccz .LBB0_2602
	v_pk_mul_f32 v[80:81], v[80:81], v[2:3] op_sel_hi:[1,0]
	v_pk_mul_f32 v[78:79], v[78:79], v[2:3] op_sel_hi:[1,0]
	v_pk_mul_f32 v[76:77], v[76:77], v[2:3] op_sel_hi:[1,0]
	v_pk_mul_f32 v[74:75], v[74:75], v[2:3] op_sel_hi:[1,0]
	v_pk_mul_f32 v[72:73], v[72:73], v[2:3] op_sel_hi:[1,0]
	v_pk_mul_f32 v[70:71], v[70:71], v[2:3] op_sel_hi:[1,0]
	v_pk_mul_f32 v[68:69], v[68:69], v[2:3] op_sel_hi:[1,0]
	v_pk_mul_f32 v[66:67], v[66:67], v[2:3] op_sel_hi:[1,0]
	v_pk_mul_f32 v[64:65], v[64:65], v[2:3] op_sel_hi:[1,0]
	v_pk_mul_f32 v[62:63], v[62:63], v[2:3] op_sel_hi:[1,0]
	v_pk_mul_f32 v[60:61], v[60:61], v[2:3] op_sel_hi:[1,0]
	v_pk_mul_f32 v[58:59], v[58:59], v[2:3] op_sel_hi:[1,0]
	v_pk_mul_f32 v[56:57], v[56:57], v[2:3] op_sel_hi:[1,0]
	v_pk_mul_f32 v[54:55], v[54:55], v[2:3] op_sel_hi:[1,0]
	v_pk_mul_f32 v[52:53], v[52:53], v[2:3] op_sel_hi:[1,0]
	v_pk_mul_f32 v[50:51], v[50:51], v[2:3] op_sel_hi:[1,0]
	v_pk_mul_f32 v[48:49], v[48:49], v[2:3] op_sel_hi:[1,0]
	v_pk_mul_f32 v[46:47], v[46:47], v[2:3] op_sel_hi:[1,0]
	v_pk_mul_f32 v[44:45], v[44:45], v[2:3] op_sel_hi:[1,0]
	v_pk_mul_f32 v[42:43], v[42:43], v[2:3] op_sel_hi:[1,0]
	v_pk_mul_f32 v[40:41], v[40:41], v[2:3] op_sel_hi:[1,0]
	v_pk_mul_f32 v[38:39], v[38:39], v[2:3] op_sel_hi:[1,0]
	v_pk_mul_f32 v[36:37], v[36:37], v[2:3] op_sel_hi:[1,0]
	v_pk_mul_f32 v[34:35], v[34:35], v[2:3] op_sel_hi:[1,0]
	v_pk_mul_f32 v[32:33], v[32:33], v[2:3] op_sel_hi:[1,0]
	v_pk_mul_f32 v[30:31], v[30:31], v[2:3] op_sel_hi:[1,0]
	v_pk_mul_f32 v[28:29], v[28:29], v[2:3] op_sel_hi:[1,0]
	v_pk_mul_f32 v[26:27], v[26:27], v[2:3] op_sel_hi:[1,0]
	v_pk_mul_f32 v[24:25], v[24:25], v[2:3] op_sel_hi:[1,0]
	v_pk_mul_f32 v[22:23], v[22:23], v[2:3] op_sel_hi:[1,0]
	v_pk_mul_f32 v[20:21], v[20:21], v[2:3] op_sel_hi:[1,0]
	v_pk_mul_f32 v[18:19], v[18:19], v[2:3] op_sel_hi:[1,0]

; #define LAS __attribute__((address_space(3)))
; __device__ __forceinline__ float fexp2(float x) { return __builtin_amdgcn_exp2f(x); }
; __device__ __forceinline__ float fmax3(float a, float b, float c) { float d; asm("v_max3_f32 %0, %1, %2, %3" : "=v"(d) : "v"(a), "v"(b), "v"(c)); return d; }
; template <int MODE, int DK, bool PASS2> ...
;     ...
;                     float mx = fmaxf(s0[0], s1[0]);
; #pragma unroll
;                     for (int r = 1; r < 16; ++r) mx = fmax3(mx, s0[r], s1[r]);
;                     if (MODE == M_SLC) mx = selbit ? mx : NEG;
;                     mx = xhalf_max(mx);
;                     const float mxs = mx * sl2;
;                     const float mn = (mxs > m_run + 8.0f) ? mxs : m_run;
;                     const float alpha = fexp2(m_run - mn);
;                     m_run = mn;
;                     float nm = -mn;
;                     if (MODE == M_SLC) nm = selbit ? nm : -__builtin_inff();
;                     float ps0 = 0.f, ps1 = 0.f;
; #pragma unroll
;                     for (int r = 0; r < 16; ++r) {
;                         s0[r] = fexp2(__builtin_fmaf(s0[r], sl2, nm)); s1[r] = fexp2(__builtin_fmaf(s1[r], sl2, nm));
;                         ps0 += s0[r]; ps1 += s1[r];
;                     }
;                     l_run = l_run * alpha + (ps0 + ps1);
;                     if (__builtin_amdgcn_ballot_w64(alpha != 1.0f) != 0ull) {
; #pragma unroll
;                         for (int db = 0; db < 4; ++db)
; #pragma unroll
;                             for (int r = 0; r < 16; ++r) O[db][r] *= alpha;
;                     }
;     ...
;                     const LAS unsigned char* vb = lds + F_VB0 + buf * F_VBS + ql * 144 + g * 16;
.Lfast_slc:
	s_mul_i32 s98, s74, 0x4800
	v_add_u32_e32 v220, s98, v214
	ds_read_b128 v[222:225], v220 offset:34816
	ds_read_b128 v[226:229], v220 offset:39424
	ds_read_b128 v[230:233], v220 offset:44032
	v_max_f32_e32 v174, v98, v99
	v_max_f32_e32 v175, v82, v83
	v_max3_f32 v174, v174, v100, v101
	v_max3_f32 v175, v175, v84, v85
	v_max3_f32 v174, v174, v102, v103
	v_max3_f32 v175, v175, v86, v87
	v_max3_f32 v174, v174, v104, v105
	v_max3_f32 v175, v175, v88, v89
	v_max3_f32 v174, v174, v106, v107
	v_max3_f32 v175, v175, v90, v91
	v_max3_f32 v174, v174, v108, v109
	v_max3_f32 v175, v175, v92, v93
	v_max3_f32 v174, v174, v110, v111
	v_max3_f32 v175, v175, v94, v95
	v_max3_f32 v174, v174, v112, v113
	v_max3_f32 v175, v175, v96, v97
	v_max_f32_e32 v174, v174, v175
	v_cndmask_b32_e64 v174, v194, v174, s[4:5]
	v_mov_b32_e32 v175, v174
	s_nop 1
	v_permlane32_swap_b32_e32 v174, v175
	v_max_f32_e32 v174, v174, v175
	v_mul_f32_e32 v174, 0x3e0293ee, v174
	v_cmp_gt_f32_e32 vcc, v174, v2
	s_nop 1
	v_cndmask_b32_e32 v218, v217, v174, vcc
	v_sub_f32_e32 v175, v217, v218
	v_exp_f32_e32 v2, v175
	s_nop 0
	v_cmp_neq_f32_e32 vcc, 1.0, v2
	s_cbranch_vccz .Lfast_slc_norescale
	v_pk_mul_f32 v[80:81], v[80:81], v[2:3] op_sel_hi:[1,0]
	v_pk_mul_f32 v[78:79], v[78:79], v[2:3] op_sel_hi:[1,0]
	v_pk_mul_f32 v[76:77], v[76:77], v[2:3] op_sel_hi:[1,0]
	v_pk_mul_f32 v[74:75], v[74:75], v[2:3] op_sel_hi:[1,0]
	v_pk_mul_f32 v[72:73], v[72:73], v[2:3] op_sel_hi:[1,0]
	v_pk_mul_f32 v[70:71], v[70:71], v[2:3] op_sel_hi:[1,0]
	v_pk_mul_f32 v[68:69], v[68:69], v[2:3] op_sel_hi:[1,0]
	v_pk_mul_f32 v[66:67], v[66:67], v[2:3] op_sel_hi:[1,0]
	v_pk_mul_f32 v[64:65], v[64:65], v[2:3] op_sel_hi:[1,0]
	v_pk_mul_f32 v[62:63], v[62:63], v[2:3] op_sel_hi:[1,0]
	v_pk_mul_f32 v[60:61], v[60:61], v[2:3] op_sel_hi:[1,0]
	v_pk_mul_f32 v[58:59], v[58:59], v[2:3] op_sel_hi:[1,0]
	v_pk_mul_f32 v[56:57], v[56:57], v[2:3] op_sel_hi:[1,0]
	v_pk_mul_f32 v[54:55], v[54:55], v[2:3] op_sel_hi:[1,0]
	v_pk_mul_f32 v[52:53], v[52:53], v[2:3] op_sel_hi:[1,0]
	v_pk_mul_f32 v[50:51], v[50:51], v[2:3] op_sel_hi:[1,0]
	v_pk_mul_f32 v[48:49], v[48:49], v[2:3] op_sel_hi:[1,0]
	v_pk_mul_f32 v[46:47], v[46:47], v[2:3] op_sel_hi:[1,0]
	v_pk_mul_f32 v[44:45], v[44:45], v[2:3] op_sel_hi:[1,0]
	v_pk_mul_f32 v[42:43], v[42:43], v[2:3] op_sel_hi:[1,0]
	v_pk_mul_f32 v[40:41], v[40:41], v[2:3] op_sel_hi:[1,0]
	v_pk_mul_f32 v[38:39], v[38:39], v[2:3] op_sel_hi:[1,0]
	v_pk_mul_f32 v[36:37], v[36:37], v[2:3] op_sel_hi:[1,0]
	v_pk_mul_f32 v[34:35], v[34:35], v[2:3] op_sel_hi:[1,0]
	v_pk_mul_f32 v[32:33], v[32:33], v[2:3] op_sel_hi:[1,0]
	v_pk_mul_f32 v[30:31], v[30:31], v[2:3] op_sel_hi:[1,0]
	v_pk_mul_f32 v[28:29], v[28:29], v[2:3] op_sel_hi:[1,0]
	v_pk_mul_f32 v[26:27], v[26:27], v[2:3] op_sel_hi:[1,0]
	v_pk_mul_f32 v[24:25], v[24:25], v[2:3] op_sel_hi:[1,0]
	v_pk_mul_f32 v[22:23], v[22:23], v[2:3] op_sel_hi:[1,0]
	v_pk_mul_f32 v[20:21], v[20:21], v[2:3] op_sel_hi:[1,0]
	v_pk_mul_f32 v[18:19], v[18:19], v[2:3] op_sel_hi:[1,0]
; #define LAS __attribute__((address_space(3)))
; __device__ __forceinline__ unsigned pack2(float lo, float hi) { unsigned r; asm volatile("v_cvt_pk_bf16_f32 %0, %1, %2" : "=v"(r) : "v"(lo), "v"(hi)); return r; }
; __device__ __forceinline__ float fexp2(float x) { return __builtin_amdgcn_exp2f(x); }
; __device__ __forceinline__ f32x16 mfma32(bf16x8 a, bf16x8 b, f32x16 c) { return __builtin_amdgcn_mfma_f32_32x32x16_bf16(a, b, c, 0, 0, 0); }
; template <int MODE, int DK, bool PASS2> ...
;     ...
;                     float ps0 = 0.f, ps1 = 0.f;
; #pragma unroll
;                     for (int r = 0; r < 16; ++r) {
;                         s0[r] = fexp2(__builtin_fmaf(s0[r], sl2, nm)); s1[r] = fexp2(__builtin_fmaf(s1[r], sl2, nm));
;                         ps0 += s0[r]; ps1 += s1[r];
;                     }
;                     l_run = l_run * alpha + (ps0 + ps1);
;     ...
;                 if (!PASS2) {
;                     bf16x8 pf[4];
; #pragma unroll
;                     for (int k2 = 0; k2 < 4; ++k2) {
;                         u32x4 pk;
; #pragma unroll
;                         for (int e = 0; e < 4; ++e) pk[e] = (k2 < 2) ? pack2(s0[(k2 & 1) * 8 + 2 * e], s0[(k2 & 1) * 8 + 2 * e + 1]) : pack2(s1[(k2 & 1) * 8 + 2 * e], s1[(k2 & 1) * 8 + 2 * e + 1]);
;                         pf[k2] = __builtin_bit_cast(bf16x8, pk);
;                     }
;                     const LAS unsigned char* vb = lds + F_VB0 + buf * F_VBS + ql * 144 + g * 16;
;                     __builtin_amdgcn_s_setprio(1);
; #pragma unroll
;                     for (int db = 0; db < 4; ++db)
; #pragma unroll
;                         for (int k2 = 0; k2 < 4; ++k2) {
;                             const bf16x8 vf = *(const LAS bf16x8*)(vb + db * 32 * 144 + k2 * 32);
;                             O[db] = mfma32(vf, pf[k2], O[db]);
;                             if (k2 == 3 && (db & 1)) __builtin_amdgcn_sched_barrier(0);
;                         }
;                     __builtin_amdgcn_s_setprio(0);
.Lfast_slc_norescale:
	v_cndmask_b32_e64 v191, v195, -v218, s[4:5]
	v_fmamk_f32 v12, v98, 0x3e0293ee, v191
	v_fmamk_f32 v13, v99, 0x3e0293ee, v191
	v_exp_f32_e32 v4, v12
	v_exp_f32_e32 v5, v13
	v_fmamk_f32 v14, v100, 0x3e0293ee, v191
	v_fmamk_f32 v15, v101, 0x3e0293ee, v191
	v_exp_f32_e32 v6, v14
	v_exp_f32_e32 v7, v15
	v_add_f32_e32 v16, v4, v5
	v_fmamk_f32 v12, v102, 0x3e0293ee, v191
	v_fmamk_f32 v13, v103, 0x3e0293ee, v191
	v_exp_f32_e32 v8, v12
	v_exp_f32_e32 v9, v13
	v_cvt_pk_bf16_f32 v236, v4, v5
	v_add_f32_e32 v16, v16, v6
	v_fmamk_f32 v14, v104, 0x3e0293ee, v191
	v_add_f32_e32 v16, v16, v7
	v_fmamk_f32 v15, v105, 0x3e0293ee, v191
	v_exp_f32_e32 v10, v14
	v_exp_f32_e32 v11, v15
	v_cvt_pk_bf16_f32 v237, v6, v7
	v_add_f32_e32 v16, v16, v8
	v_add_f32_e32 v16, v16, v9
	v_cvt_pk_bf16_f32 v238, v8, v9
	v_add_f32_e32 v16, v16, v10
	v_add_f32_e32 v16, v16, v11
	v_cvt_pk_bf16_f32 v239, v10, v11
	s_setprio 1
	v_fmamk_f32 v12, v106, 0x3e0293ee, v191
	v_fmamk_f32 v13, v107, 0x3e0293ee, v191
	s_waitcnt lgkmcnt(2)
	v_mfma_f32_32x32x16_bf16 v[66:81], v[222:225], v[236:239], v[66:81]
	v_exp_f32_e32 v4, v12
	v_exp_f32_e32 v5, v13
	v_fmamk_f32 v14, v108, 0x3e0293ee, v191
	v_fmamk_f32 v15, v109, 0x3e0293ee, v191
	v_exp_f32_e32 v6, v14
	v_exp_f32_e32 v7, v15
	s_waitcnt lgkmcnt(1)
	v_mfma_f32_32x32x16_bf16 v[50:65], v[226:229], v[236:239], v[50:65]
	ds_read_b128 v[222:225], v220 offset:48640
	v_add_f32_e32 v16, v16, v4
	v_fmamk_f32 v12, v110, 0x3e0293ee, v191
	v_add_f32_e32 v16, v16, v5
	v_fmamk_f32 v13, v111, 0x3e0293ee, v191
	v_exp_f32_e32 v8, v12
	v_exp_f32_e32 v9, v13
	s_waitcnt lgkmcnt(1)
	v_mfma_f32_32x32x16_bf16 v[34:49], v[230:233], v[236:239], v[34:49]
	ds_read_b128 v[226:229], v220 offset:34848
	v_cvt_pk_bf16_f32 v240, v4, v5
	v_add_f32_e32 v16, v16, v6
	v_fmamk_f32 v14, v112, 0x3e0293ee, v191
	v_add_f32_e32 v16, v16, v7
	v_fmamk_f32 v15, v113, 0x3e0293ee, v191
	v_exp_f32_e32 v10, v14
	s_waitcnt lgkmcnt(1)
	v_mfma_f32_32x32x16_bf16 v[18:33], v[222:225], v[236:239], v[18:33]
	ds_read_b128 v[230:233], v220 offset:39456
	v_exp_f32_e32 v11, v15
	v_cvt_pk_bf16_f32 v241, v6, v7
	v_add_f32_e32 v16, v16, v8
	v_add_f32_e32 v16, v16, v9
	v_cvt_pk_bf16_f32 v242, v8, v9
	v_add_f32_e32 v16, v16, v10
	v_add_f32_e32 v16, v16, v11
	v_cvt_pk_bf16_f32 v243, v10, v11
	v_fmamk_f32 v12, v82, 0x3e0293ee, v191
	v_fmamk_f32 v13, v83, 0x3e0293ee, v191
	s_waitcnt lgkmcnt(1)
	v_mfma_f32_32x32x16_bf16 v[66:81], v[226:229], v[240:243], v[66:81]
	ds_read_b128 v[222:225], v220 offset:44064
	v_exp_f32_e32 v4, v12
	v_exp_f32_e32 v5, v13
	v_fmamk_f32 v14, v84, 0x3e0293ee, v191
	v_fmamk_f32 v15, v85, 0x3e0293ee, v191
	v_exp_f32_e32 v6, v14
	v_exp_f32_e32 v7, v15
	s_waitcnt lgkmcnt(1)
	v_mfma_f32_32x32x16_bf16 v[50:65], v[230:233], v[240:243], v[50:65]
	ds_read_b128 v[226:229], v220 offset:48672
	v_add_f32_e32 v17, v4, v5
	v_fmamk_f32 v12, v86, 0x3e0293ee, v191
	v_fmamk_f32 v13, v87, 0x3e0293ee, v191
	v_exp_f32_e32 v8, v12
	v_exp_f32_e32 v9, v13
	v_cvt_pk_bf16_f32 v244, v4, v5
	s_waitcnt lgkmcnt(1)
	v_mfma_f32_32x32x16_bf16 v[34:49], v[222:225], v[240:243], v[34:49]
	ds_read_b128 v[230:233], v220 offset:34880
	v_add_f32_e32 v17, v17, v6
	v_fmamk_f32 v14, v88, 0x3e0293ee, v191
	v_add_f32_e32 v17, v17, v7
	v_fmamk_f32 v15, v89, 0x3e0293ee, v191
	v_exp_f32_e32 v10, v14
	v_exp_f32_e32 v11, v15
	s_waitcnt lgkmcnt(1)
	v_mfma_f32_32x32x16_bf16 v[18:33], v[226:229], v[240:243], v[18:33]
	ds_read_b128 v[222:225], v220 offset:39488
	v_cvt_pk_bf16_f32 v245, v6, v7
	v_add_f32_e32 v17, v17, v8
	v_add_f32_e32 v17, v17, v9
	v_cvt_pk_bf16_f32 v246, v8, v9
	v_add_f32_e32 v17, v17, v10
	v_add_f32_e32 v17, v17, v11
	v_cvt_pk_bf16_f32 v247, v10, v11
	v_fmamk_f32 v12, v90, 0x3e0293ee, v191
	v_fmamk_f32 v13, v91, 0x3e0293ee, v191
	s_waitcnt lgkmcnt(1)
	v_mfma_f32_32x32x16_bf16 v[66:81], v[230:233], v[244:247], v[66:81]
	ds_read_b128 v[226:229], v220 offset:44096
	v_exp_f32_e32 v4, v12
	v_exp_f32_e32 v5, v13
	v_fmamk_f32 v14, v92, 0x3e0293ee, v191
	v_fmamk_f32 v15, v93, 0x3e0293ee, v191
	v_exp_f32_e32 v6, v14
	v_exp_f32_e32 v7, v15
	s_waitcnt lgkmcnt(1)
	v_mfma_f32_32x32x16_bf16 v[50:65], v[222:225], v[244:247], v[50:65]
	ds_read_b128 v[230:233], v220 offset:48704
	v_add_f32_e32 v17, v17, v4
	v_fmamk_f32 v12, v94, 0x3e0293ee, v191
	v_add_f32_e32 v17, v17, v5
	v_fmamk_f32 v13, v95, 0x3e0293ee, v191
	v_exp_f32_e32 v8, v12
	v_exp_f32_e32 v9, v13
	s_waitcnt lgkmcnt(1)
	v_mfma_f32_32x32x16_bf16 v[34:49], v[226:229], v[244:247], v[34:49]
	ds_read_b128 v[222:225], v220 offset:34912
	v_cvt_pk_bf16_f32 v248, v4, v5
	v_add_f32_e32 v17, v17, v6
	v_fmamk_f32 v14, v96, 0x3e0293ee, v191
	v_add_f32_e32 v17, v17, v7
	v_fmamk_f32 v15, v97, 0x3e0293ee, v191
	v_exp_f32_e32 v10, v14
	s_waitcnt lgkmcnt(1)
	v_mfma_f32_32x32x16_bf16 v[18:33], v[230:233], v[244:247], v[18:33]
	ds_read_b128 v[226:229], v220 offset:39520
	v_exp_f32_e32 v11, v15
	v_cvt_pk_bf16_f32 v249, v6, v7
	v_add_f32_e32 v17, v17, v8
	v_add_f32_e32 v17, v17, v9
	v_cvt_pk_bf16_f32 v250, v8, v9
	v_add_f32_e32 v17, v17, v10
	v_add_f32_e32 v17, v17, v11
	v_cvt_pk_bf16_f32 v251, v10, v11
	v_add_f32_e32 v219, v16, v17
	s_waitcnt lgkmcnt(1)
	v_mfma_f32_32x32x16_bf16 v[66:81], v[222:225], v[248:251], v[66:81]
	ds_read_b128 v[230:233], v220 offset:44128
	v_fmac_f32_e32 v219, v216, v2
	s_waitcnt lgkmcnt(1)
	v_mfma_f32_32x32x16_bf16 v[50:65], v[226:229], v[248:251], v[50:65]
	ds_read_b128 v[222:225], v220 offset:48736
	s_waitcnt lgkmcnt(1)
	v_mfma_f32_32x32x16_bf16 v[34:49], v[230:233], v[248:251], v[34:49]
	s_waitcnt lgkmcnt(0)
	v_mfma_f32_32x32x16_bf16 v[18:33], v[222:225], v[248:251], v[18:33]
	s_setprio 0
	s_branch .Lpostpv_slc
